# stacked small changes on the queue-tail version: nt loads for the read-once gate columns in the branch-GEMM epilogue, static priority raise for waves 4-7 inside the MLA tile loop only
# speedup vs baseline: 1.0008x; 1.0008x over previous
; #define LAS __attribute__((address_space(3)))
; #define ATT_WAIT_TILE() do { if (FOX) { if (w == 0) asm volatile("s_waitcnt vmcnt(3)" ::: "memory"); else asm volatile("s_waitcnt vmcnt(2)" ::: "memory"); } \
;                              else asm volatile("s_waitcnt vmcnt(5)" ::: "memory"); } while (0)
; template <int DQK, int DV, bool FOX> ...
;     ...
;     const int tid = threadIdx.x, lane = tid & 63, r = lane & 31, h = lane >> 5; const int w = __builtin_amdgcn_readfirstlane(tid >> 6);
;     const int q0 = qb * 256;
;     const int NT = 4 * qb + 4, ntw = 4 * qb + (w >> 1) + 1;
;     LAS float* wsf = (LAS float*)(lds + WS_OFF) + w * 64;
;     bf16x8 qf[ND0];
;     { const bf16_t* qp = Q + (size_t)(q0 + 32 * w + r) * ldq + 8 * h;
; #pragma unroll
;       for (int d0 = 0; d0 < ND0; ++d0) qf[d0] = *(const bf16x8*)(qp + 16 * d0); }
;     float cq = 0.f, basev = 0.f;
;     if (FOX) {
;         const float tv = tot[lane]; float incl = tv;
; #pragma unroll
;         for (int o_ = 1; o_ < 64; o_ <<= 1) { const float t_ = __shfl_up(incl, o_); if (lane >= o_) incl += t_; }
;         basev = incl - tv;
;         cq = cum[q0 + 32 * w + r] + __builtin_bit_cast(float, __builtin_amdgcn_readlane(__builtin_bit_cast(int, basev), 4 * qb + (w >> 1)));
;     }
;     ...
;     const unsigned lds_u = (unsigned)(uintptr_t)lds;
;     f32x16 o[NCB];
; #pragma unroll
;     for (int cb = 0; cb < NCB; ++cb)
; #pragma unroll
;         for (int i = 0; i < 16; ++i) o[cb][i] = 0.f;
;     float mref = -1e30f, lsum = 0.f;
;     const int kread0 = r * KROW;
;     const int ksw = (r >> 1) & 7;
;     const int vread0 = KT_BYTES + ((lane >> 4) & 1) * 32 + (lane & 3) * 8 + (4 * h + ((lane & 15) >> 2)) * 64;
;     ...
;     ATT_DMA(0, 0); ATT_DMA(1, 1); ATT_WAIT_TILE(); __builtin_amdgcn_s_barrier();
.LBB0_679:
	s_and_b64 vcc, exec, s[0:1]
	s_cbranch_vccz .LBB0_641
	s_lshl_b32 s26, s8, 9
	s_and_b32 s7, s26, 0x1000
	s_and_b32 s4, s8, 7
	s_mul_i32 s0, s7, 0xc00
	v_readlane_b32 s1, v255, 18
	s_add_u32 s0, s1, s0
	v_readlane_b32 s1, v255, 19
	s_addc_u32 s1, s1, 0
	s_mul_i32 s2, s4, 0x180
	s_add_u32 s0, s0, s2
	s_addc_u32 s1, s1, 0
	s_lshl_b32 s2, s7, 12
	v_readlane_b32 s3, v255, 20
	s_add_u32 s2, s3, s2
	v_readlane_b32 s3, v255, 21
	s_addc_u32 s3, s3, 0
	s_lshl_b32 s5, s4, 9
	s_add_u32 s22, s2, s5
	s_addc_u32 s23, s3, 0
	s_lshl_b32 s28, s7, 7
	v_readlane_b32 s2, v255, 14
	s_add_u32 s2, s2, s28
	v_readlane_b32 s3, v255, 15
	v_readfirstlane_b32 s27, v0
	s_addc_u32 s3, s3, 0
	s_lshr_b32 s9, s27, 6
	s_lshl_b32 s5, s39, 8
	s_lshl_b32 s8, s9, 5
	s_add_i32 s20, s8, s5
	v_or_b32_e32 v4, s20, v146
	v_mov_b64_e32 v[2:3], s[0:1]
	s_movk_i32 s0, 0xc00
	v_mad_u64_u32 v[2:3], s[0:1], v4, s0, v[2:3]
	v_lshl_add_u64 v[2:3], v[2:3], 0, v[150:151]
	global_load_dwordx4 v[98:101], v[2:3], off
	global_load_dwordx4 v[102:105], v[2:3], off offset:32
	global_load_dwordx4 v[106:109], v[2:3], off offset:64
	global_load_dwordx4 v[110:113], v[2:3], off offset:96
	global_load_dwordx4 v[114:117], v[2:3], off offset:128
	global_load_dwordx4 v[118:121], v[2:3], off offset:160
	global_load_dwordx4 v[122:125], v[2:3], off offset:192
	global_load_dwordx4 v[126:129], v[2:3], off offset:224
	global_load_dwordx4 v[130:133], v[2:3], off offset:256
	global_load_dwordx4 v[134:137], v[2:3], off offset:288
	global_load_dwordx4 v[138:141], v[2:3], off offset:320
	global_load_dwordx4 v[142:145], v[2:3], off offset:352
	s_and_b32 s29, s27, 0xffffffc0
	v_or_b32_e32 v2, s29, v196
	v_mul_hi_u32 v3, v2, s33
	v_lshrrev_b32_e32 v14, 4, v3
	v_mul_lo_u32 v4, v14, 24
	v_sub_u32_e32 v24, v2, v4
	v_lshrrev_b32_e32 v2, 5, v3
	v_bitop3_b32 v25, v2, 7, v24 bitop3:0x48
	v_and_or_b32 v2, v24, 24, v25
	v_mov_b32_e32 v15, v151
	v_lshlrev_b32_e32 v4, 3, v2
	v_cmp_gt_u32_e64 s[14:15], 16, v24
	v_lshlrev_b64 v[2:3], 12, v[14:15]
	v_lshlrev_b32_e32 v150, 1, v4
	s_and_saveexec_b64 s[0:1], s[14:15]
	s_xor_b64 s[0:1], exec, s[0:1]
	v_lshl_add_u64 v[4:5], s[22:23], 0, v[2:3]
	v_lshl_add_u64 v[4:5], v[4:5], 0, v[150:151]
	s_or_saveexec_b64 s[0:1], s[0:1]
	v_lshlrev_b64 v[6:7], 7, v[14:15]
	s_xor_b64 exec, exec, s[0:1]
	v_lshl_add_u64 v[4:5], s[2:3], 0, v[6:7]
	v_lshl_add_u64 v[4:5], v[4:5], 0, v[150:151]
	v_lshl_add_u64 v[4:5], v[4:5], 0, s[40:41]
	s_or_b64 exec, exec, s[0:1]
	s_lshl_b32 s5, s9, 10
	s_add_i32 s24, s9, 8
	s_add_i32 s11, s5, 0
	s_mov_b32 s0, m0
	s_mov_b32 m0, s11
	s_nop 0
	global_load_lds_dwordx4 v[4:5], off
	s_mov_b32 m0, s0
	v_lshl_or_b32 v4, s24, 6, v196
	v_mul_hi_u32 v5, v4, s33
	v_lshrrev_b32_e32 v16, 4, v5
	v_mul_lo_u32 v8, v16, 24
	v_sub_u32_e32 v26, v4, v8
	v_lshrrev_b32_e32 v4, 5, v5
	v_bitop3_b32 v27, v4, 7, v26 bitop3:0x48
	v_and_or_b32 v4, v26, 24, v27
	v_mov_b32_e32 v17, v151
	v_lshlrev_b32_e32 v8, 3, v4
	v_cmp_gt_u32_e64 s[16:17], 16, v26
	v_lshlrev_b64 v[4:5], 12, v[16:17]
	v_lshlrev_b32_e32 v192, 1, v8
	s_and_saveexec_b64 s[0:1], s[16:17]
	s_xor_b64 s[0:1], exec, s[0:1]
	v_lshl_add_u64 v[8:9], s[22:23], 0, v[4:5]
	v_mov_b32_e32 v193, v151
	v_lshl_add_u64 v[8:9], v[8:9], 0, v[192:193]
	s_or_saveexec_b64 s[0:1], s[0:1]
	v_lshlrev_b64 v[10:11], 7, v[16:17]
	s_xor_b64 exec, exec, s[0:1]
	v_lshl_add_u64 v[8:9], s[2:3], 0, v[10:11]
	v_mov_b32_e32 v193, v151
	v_lshl_add_u64 v[8:9], v[8:9], 0, v[192:193]
	v_lshl_add_u64 v[8:9], v[8:9], 0, s[40:41]
	s_or_b64 exec, exec, s[0:1]
	s_lshl_b32 s8, s24, 10
	s_add_i32 s21, s9, 16
	s_add_i32 s30, s8, 0
	s_mov_b32 s0, m0
	s_mov_b32 m0, s30
	s_nop 0
	global_load_lds_dwordx4 v[8:9], off
	s_mov_b32 m0, s0
	v_lshl_or_b32 v8, s21, 6, v196
	v_mul_hi_u32 v9, v8, s33
	v_lshrrev_b32_e32 v20, 4, v9
	v_mul_lo_u32 v12, v20, 24
	v_sub_u32_e32 v28, v8, v12
	v_lshrrev_b32_e32 v8, 5, v9
	v_bitop3_b32 v29, v8, 7, v28 bitop3:0x48
	v_and_or_b32 v8, v28, 24, v29
	v_mov_b32_e32 v21, v151
	v_lshlrev_b32_e32 v12, 3, v8
	v_cmp_gt_u32_e64 s[18:19], 16, v28
	v_lshlrev_b64 v[8:9], 12, v[20:21]
	v_lshlrev_b32_e32 v194, 1, v12
	s_and_saveexec_b64 s[0:1], s[18:19]
	s_xor_b64 s[0:1], exec, s[0:1]
	v_lshl_add_u64 v[12:13], s[22:23], 0, v[8:9]
	v_mov_b32_e32 v195, v151
	v_lshl_add_u64 v[18:19], v[12:13], 0, v[194:195]
	s_or_saveexec_b64 s[0:1], s[0:1]
	v_lshlrev_b64 v[12:13], 7, v[20:21]
	s_xor_b64 exec, exec, s[0:1]
	v_lshl_add_u64 v[18:19], s[2:3], 0, v[12:13]
	v_mov_b32_e32 v195, v151
	v_lshl_add_u64 v[18:19], v[18:19], 0, v[194:195]
	v_lshl_add_u64 v[18:19], v[18:19], 0, s[40:41]
	s_or_b64 exec, exec, s[0:1]
	s_lshl_b32 s21, s21, 10
	s_add_i32 s31, s21, 0
	s_mov_b32 s0, m0
	s_mov_b32 m0, s31
	s_nop 0
	global_load_lds_dwordx4 v[18:19], off
	s_mov_b32 m0, s0
	s_lshl_b32 s0, s9, 4
	v_and_or_b32 v15, s0, 48, v155
	v_lshlrev_b32_e32 v18, 12, v15
	v_mov_b32_e32 v19, v151
	v_lshl_add_u64 v[18:19], s[22:23], 0, v[18:19]
	v_mov_b32_e32 v191, v151
	v_lshl_add_u64 v[22:23], v[18:19], 0, v[190:191]
	s_mov_b64 s[0:1], 0x100
	v_lshl_add_u64 v[22:23], v[22:23], 0, s[0:1]
	s_lshl_b32 s0, s9, 3
	s_and_b32 s0, s0, 0x1fffffe0
	v_readlane_b32 s9, v255, 36
	s_lshl_b32 s84, s0, 1
	s_add_i32 s0, s5, s9
	v_lshl_add_u64 v[30:31], v[22:23], 0, s[84:85]
	s_mov_b32 s1, m0
	s_mov_b32 m0, s0
	s_nop 0
	global_load_lds_dwordx4 v[30:31], off
	s_mov_b32 m0, s1
	s_lshl_b32 s0, s24, 3
	s_and_b32 s0, s0, 0x3fffffe0
	s_lshl_b32 s0, s0, 1
	s_mov_b32 s1, s85
	v_lshl_add_u64 v[22:23], v[22:23], 0, s[0:1]
	s_add_i32 s1, s8, s9
	s_mov_b32 s9, m0
	s_mov_b32 m0, s1
	s_nop 0
	global_load_lds_dwordx4 v[22:23], off
	s_mov_b32 m0, s9
	v_add_u32_e32 v22, 64, v14
	v_mov_b32_e32 v23, v151
	s_and_saveexec_b64 s[24:25], s[14:15]
; #define ATT_WAIT_TILE() do { if (FOX) { if (w == 0) asm volatile("s_waitcnt vmcnt(3)" ::: "memory"); else asm volatile("s_waitcnt vmcnt(2)" ::: "memory"); } \
;                              else asm volatile("s_waitcnt vmcnt(5)" ::: "memory"); } while (0)
; template <int DQK, int DV, bool FOX> ...
;     ...
;     const unsigned lds_u = (unsigned)(uintptr_t)lds;
;     f32x16 o[NCB];
; #pragma unroll
;     for (int cb = 0; cb < NCB; ++cb)
; #pragma unroll
;         for (int i = 0; i < 16; ++i) o[cb][i] = 0.f;
;     float mref = -1e30f, lsum = 0.f;
;     const int kread0 = r * KROW;
;     const int ksw = (r >> 1) & 7;
;     const int vread0 = KT_BYTES + ((lane >> 4) & 1) * 32 + (lane & 3) * 8 + (4 * h + ((lane & 15) >> 2)) * 64;
;     ...
;     ATT_DMA(0, 0); ATT_DMA(1, 1); ATT_WAIT_TILE(); __builtin_amdgcn_s_barrier();
; #pragma unroll
;     for (int d0 = 0; d0 < ND0; ++d0) asm volatile("" : "+v"(qf[d0]));
;     if (FOX) asm volatile("" : "+v"(cq), "+v"(basev));
;     int bc = 0, bn2 = 2;
	s_xor_b64 s[24:25], exec, s[24:25]
	v_lshlrev_b64 v[14:15], 12, v[22:23]
	v_lshl_add_u64 v[14:15], s[22:23], 0, v[14:15]
	v_lshl_add_u64 v[14:15], v[14:15], 0, v[150:151]
	s_andn2_saveexec_b64 s[24:25], s[24:25]
	v_lshlrev_b64 v[14:15], 7, v[22:23]
	v_lshl_add_u64 v[14:15], s[2:3], 0, v[14:15]
	v_lshl_add_u64 v[14:15], v[14:15], 0, v[150:151]
	v_lshl_add_u64 v[14:15], v[14:15], 0, s[40:41]
	s_or_b64 exec, exec, s[24:25]
	s_add_i32 s11, s11, 0xa100
	s_mov_b32 s1, m0
	s_mov_b32 m0, s11
	s_nop 0
	global_load_lds_dwordx4 v[14:15], off
	s_mov_b32 m0, s1
	v_add_u32_e32 v16, 64, v16
	v_mov_b32_e32 v17, v151
	s_and_saveexec_b64 s[24:25], s[16:17]
	s_xor_b64 s[24:25], exec, s[24:25]
	v_lshlrev_b64 v[14:15], 12, v[16:17]
	v_lshl_add_u64 v[14:15], s[22:23], 0, v[14:15]
	v_mov_b32_e32 v193, v151
	v_lshl_add_u64 v[14:15], v[14:15], 0, v[192:193]
	s_andn2_saveexec_b64 s[24:25], s[24:25]
	v_lshlrev_b64 v[14:15], 7, v[16:17]
	v_lshl_add_u64 v[14:15], s[2:3], 0, v[14:15]
	v_mov_b32_e32 v193, v151
	v_lshl_add_u64 v[14:15], v[14:15], 0, v[192:193]
	v_lshl_add_u64 v[14:15], v[14:15], 0, s[40:41]
	s_or_b64 exec, exec, s[24:25]
	s_add_i32 s30, s30, 0xa100
	s_mov_b32 s1, m0
	s_mov_b32 m0, s30
	s_nop 0
	global_load_lds_dwordx4 v[14:15], off
	s_mov_b32 m0, s1
	v_add_u32_e32 v16, 64, v20
	v_mov_b32_e32 v17, v151
	s_and_saveexec_b64 s[24:25], s[18:19]
	s_xor_b64 s[24:25], exec, s[24:25]
	v_lshlrev_b64 v[14:15], 12, v[16:17]
	v_lshl_add_u64 v[14:15], s[22:23], 0, v[14:15]
	v_mov_b32_e32 v195, v151
	v_lshl_add_u64 v[14:15], v[14:15], 0, v[194:195]
	s_or_saveexec_b64 s[22:23], s[24:25]
	s_lshl_b32 s9, s7, 11
	s_xor_b64 exec, exec, s[22:23]
	v_lshlrev_b64 v[14:15], 7, v[16:17]
	v_lshl_add_u64 v[14:15], s[2:3], 0, v[14:15]
	v_mov_b32_e32 v195, v151
	v_lshl_add_u64 v[14:15], v[14:15], 0, v[194:195]
	v_lshl_add_u64 v[14:15], v[14:15], 0, s[40:41]
	s_or_b64 exec, exec, s[22:23]
	s_add_i32 s31, s31, 0xa100
	s_mov_b32 s1, m0
	s_mov_b32 m0, s31
	s_nop 0
	global_load_lds_dwordx4 v[14:15], off
	s_mov_b32 m0, s1
	v_mov_b32_e32 v191, v151
	s_lshl_b32 s1, s29, 2
	v_lshl_add_u64 v[14:15], v[18:19], 0, v[190:191]
	s_mov_b64 s[2:3], 0x40100
	s_add_i32 s1, s1, 0
	v_lshl_add_u64 v[14:15], v[14:15], 0, s[2:3]
	v_readlane_b32 s3, v255, 37
	s_add_i32 s22, s1, 0x1e300
	s_add_i32 s1, s5, s3
	s_lshl_b32 s24, s39, 2
	s_lshr_b32 s7, s27, 7
	v_lshl_add_u64 v[16:17], v[14:15], 0, s[84:85]
	s_mov_b32 s2, m0
	s_mov_b32 m0, s1
	s_nop 0
	global_load_lds_dwordx4 v[16:17], off
	s_mov_b32 m0, s2
	s_mov_b32 s1, s85
	s_add_i32 s7, s7, s24
	s_add_i32 s24, s24, 4
	v_lshl_add_u64 v[14:15], v[14:15], 0, s[0:1]
	s_add_i32 s1, s8, s3
	s_mov_b32 s2, m0
	s_mov_b32 m0, s1
	s_nop 0
	global_load_lds_dwordx4 v[14:15], off
	s_mov_b32 m0, s2
	s_add_u32 s2, s28, 0x604000
	s_addc_u32 s3, 0, 0
	v_lshlrev_b32_e32 v14, 4, v25
	v_lshlrev_b32_e32 v15, 4, v24
	s_movk_i32 s1, 0x180
	v_lshl_add_u64 v[6:7], s[2:3], 0, v[6:7]
	v_and_or_b32 v14, v15, s1, v14
	v_mov_b32_e32 v15, v151
	v_lshl_add_u64 v[190:191], v[6:7], 0, v[14:15]
	v_lshl_add_u64 v[6:7], s[2:3], 0, v[10:11]
	v_lshlrev_b32_e32 v10, 4, v27
	v_lshlrev_b32_e32 v11, 4, v26
	v_and_or_b32 v10, v11, s1, v10
	v_mov_b32_e32 v11, v151
	v_lshl_add_u64 v[198:199], v[6:7], 0, v[10:11]
	v_lshlrev_b32_e32 v10, 4, v29
	v_lshlrev_b32_e32 v11, 4, v28
	v_lshl_add_u64 v[6:7], s[2:3], 0, v[12:13]
	v_and_or_b32 v10, v11, s1, v10
	s_lshl_b32 s1, s26, 12
	s_and_b32 s2, s6, 7
	s_and_b32 s1, s1, 0x1000000
	s_lshl_b32 s6, s2, 9
	v_mov_b32_e32 v11, v151
	s_or_b32 s2, s6, s1
	s_mov_b32 s3, s85
	v_lshl_add_u64 v[200:201], v[6:7], 0, v[10:11]
	v_lshl_add_u64 v[6:7], s[2:3], 0, v[188:189]
	s_lshl_b32 s2, s27, 10
	s_and_b32 s2, s2, 0x30000
	v_lshlrev_b32_e32 v10, 11, v155
	v_lshl_or_b32 v10, v10, 1, s2
	s_add_u32 s2, s1, 0x13480000
	s_waitcnt vmcnt(5)
	s_addc_u32 s3, 0, 0
	v_mov_b32_e32 v16, v151
	v_mov_b32_e32 v17, v151
	v_lshl_add_u64 v[202:203], v[6:7], 0, v[10:11]
	v_lshl_add_u64 v[204:205], s[2:3], 0, v[2:3]
	v_lshl_add_u64 v[206:207], s[2:3], 0, v[4:5]
	v_lshl_add_u64 v[208:209], s[2:3], 0, v[8:9]
	v_mov_b32_e32 v2, v151
	v_mov_b32_e32 v3, v151
	v_mov_b32_e32 v4, v151
	v_mov_b32_e32 v5, v151
	v_mov_b32_e32 v6, v151
	v_mov_b32_e32 v7, v151
	v_mov_b32_e32 v8, v151
	v_mov_b32_e32 v9, v151
	v_mov_b32_e32 v10, v151
	v_mov_b32_e32 v12, v151
	v_mov_b32_e32 v13, v151
	v_mov_b32_e32 v14, v151
	v_mov_b64_e32 v[32:33], v[16:17]
	v_mov_b64_e32 v[48:49], v[16:17]
	v_mov_b64_e32 v[64:65], v[16:17]
	s_mov_b32 s11, 2
	v_lshl_add_u32 v231, v146, 2, s22
	v_lshl_add_u32 v230, v147, 2, s22
	v_or_b32_e32 v204, s6, v204
	v_or_b32_e32 v206, s6, v206
	v_or_b32_e32 v208, s6, v208
	s_mov_b32 s6, 0
	v_mov_b32_e32 v233, 0xf149f2ca
	v_mov_b32_e32 v232, 0
	v_mov_b64_e32 v[30:31], v[14:15]
	v_mov_b64_e32 v[28:29], v[12:13]
	v_mov_b64_e32 v[26:27], v[10:11]
	v_mov_b64_e32 v[24:25], v[8:9]
	v_mov_b64_e32 v[22:23], v[6:7]
	v_mov_b64_e32 v[20:21], v[4:5]
	v_mov_b64_e32 v[18:19], v[2:3]
	v_mov_b64_e32 v[46:47], v[14:15]
	v_mov_b64_e32 v[44:45], v[12:13]
	v_mov_b64_e32 v[42:43], v[10:11]
	v_mov_b64_e32 v[40:41], v[8:9]
	v_mov_b64_e32 v[38:39], v[6:7]
	v_mov_b64_e32 v[36:37], v[4:5]
	v_mov_b64_e32 v[34:35], v[2:3]
	v_mov_b64_e32 v[62:63], v[14:15]
	v_mov_b64_e32 v[60:61], v[12:13]
	v_mov_b64_e32 v[58:59], v[10:11]
	v_mov_b64_e32 v[56:57], v[8:9]
	v_mov_b64_e32 v[54:55], v[6:7]
	v_mov_b64_e32 v[52:53], v[4:5]
	v_mov_b64_e32 v[50:51], v[2:3]
	s_mov_b32 s25, 0
	s_barrier
	s_waitcnt vmcnt(11)
	s_waitcnt vmcnt(10)
	s_waitcnt vmcnt(9)
	s_waitcnt vmcnt(8)
	s_waitcnt vmcnt(7)
	s_waitcnt vmcnt(6)
	s_waitcnt vmcnt(5)
	s_waitcnt vmcnt(4)
	s_waitcnt vmcnt(3)
	s_waitcnt vmcnt(2)
	s_waitcnt vmcnt(1)
	s_waitcnt vmcnt(0)
	s_and_b32 s98, s96, 4
	s_cmp_lg_u32 s98, 0
	s_cbranch_scc0 .Lmla_prio_skip
	s_setprio 1
.Lmla_prio_skip:
	s_branch .LBB0_706

; template <int DQK, int DV, bool FOX> ...
;     ...
;     lsum += __shfl_xor(lsum, 32);
;     if (h == 0) wsf[r] = 1.0f / lsum;
;     asm volatile("s_waitcnt lgkmcnt(0)" ::: "memory");
.LBB0_731:
	s_setprio 0
	v_and_b32_e32 v67, 64, v228
	v_xor_b32_e32 v66, 32, v228
	v_add_u32_e32 v67, 64, v67
	v_cmp_lt_i32_e32 vcc, v66, v67
	s_nop 1
	v_cndmask_b32_e32 v66, v228, v66, vcc
	v_lshlrev_b32_e32 v66, 2, v66
	ds_bpermute_b32 v66, v66, v232
	s_and_saveexec_b64 s[0:1], s[12:13]
	s_cbranch_execz .LBB0_640
	s_waitcnt lgkmcnt(0)
	v_add_f32_e32 v66, v232, v66
	v_div_scale_f32 v67, s[2:3], v66, v66, 1.0
	v_rcp_f32_e32 v68, v67
	v_div_scale_f32 v69, vcc, 1.0, v66, 1.0
	v_fma_f32 v70, -v67, v68, 1.0
	v_fmac_f32_e32 v68, v70, v68
	v_mul_f32_e32 v70, v69, v68
	v_fma_f32 v71, -v67, v70, v69
	v_fmac_f32_e32 v70, v71, v68
	v_fma_f32 v67, -v67, v70, v69
	v_div_fmas_f32 v67, v67, v68, v70
	v_div_fixup_f32 v66, v67, v66, 1.0
	ds_write_b32 v231, v66
	s_branch .LBB0_640

;     __device__ __forceinline__ void operator()(const Acc& acc, const Unit& u, int wr, int wc, int fr, int fq) const {
;     ...
;             for (int m = 0; m < 4; ++m) { const int row = row0 + ai * HALF + m * 16; const bf16_t* gp = proj + (size_t)row * NPROJ + gcol; const bf16_t* rowp = O + (size_t)row * DMODEL + col0;
; #pragma unroll
;                 for (int bj = 0; bj < 2; ++bj) { gwv[m][bj] = *(const u32x4*)(gp + bj * HALF); if (u.sel) pwv[m][bj] = *(const u32x4*)(rowp + bj * HALF); else pwv[m][bj] = (u32x4){0u, 0u, 0u, 0u}; } }
.LBB0_803:
	s_cmp_lg_u32 s5, 0
	v_lshl_add_u32 v216, s24, 8, v1
	s_cselect_b64 s[24:25], -1, 0
	s_cmp_eq_u32 s5, 0
	v_lshl_or_b32 v214, s4, 8, v232
	s_cselect_b64 s[4:5], -1, 0
	s_and_b64 vcc, s[4:5], exec
	s_cselect_b32 s4, s49, 0x1800
	v_add_u32_e32 v130, s4, v214
	v_ashrrev_i32_e32 v131, 31, v130
	v_ashrrev_i32_e32 v217, 31, v216
	v_lshl_add_u64 v[218:219], v[130:131], 1, s[8:9]
	v_lshlrev_b64 v[130:131], 14, v[216:217]
	v_lshl_add_u64 v[132:133], v[218:219], 0, v[130:131]
	global_load_dwordx4 v[192:195], v[132:133], off nt
	v_ashrrev_i32_e32 v215, 31, v214
	v_lshl_add_u64 v[220:221], v[214:215], 1, s[10:11]
	v_lshlrev_b64 v[228:229], 12, v[216:217]
	v_lshl_add_u64 v[130:131], v[220:221], 0, v[228:229]
	v_mov_b32_e32 v164, 0
	v_mov_b32_e32 v188, 0
	v_mov_b32_e32 v189, 0
	v_mov_b32_e32 v190, 0
	v_mov_b32_e32 v191, 0
	s_cbranch_vccnz .LBB0_805
	global_load_dwordx4 v[188:191], v[130:131], off nt
.LBB0_805:
	global_load_dwordx4 v[184:187], v[132:133], off offset:256 nt
	v_cndmask_b32_e64 v132, 0, 1, s[24:25]
	v_cmp_ne_u32_e64 s[4:5], 1, v132
	s_andn2_b64 vcc, exec, s[24:25]
	v_mov_b32_e32 v180, 0
	v_mov_b32_e32 v181, 0
	v_mov_b32_e32 v182, 0
	v_mov_b32_e32 v183, 0
	s_cbranch_vccnz .LBB0_807
	global_load_dwordx4 v[180:183], v[130:131], off offset:256 nt
.LBB0_807:
	v_or_b32_e32 v130, 16, v216
	v_ashrrev_i32_e32 v131, 31, v130
	v_lshlrev_b64 v[132:133], 14, v[130:131]
	v_lshl_add_u64 v[132:133], v[218:219], 0, v[132:133]
	global_load_dwordx4 v[176:179], v[132:133], off nt
	v_lshlrev_b64 v[226:227], 12, v[130:131]
	v_lshl_add_u64 v[130:131], v[220:221], 0, v[226:227]
	s_and_b64 vcc, exec, s[4:5]
	v_mov_b32_e32 v165, 0
	v_mov_b32_e32 v166, 0
	v_mov_b32_e32 v167, 0
	s_cbranch_vccnz .LBB0_809
	global_load_dwordx4 v[164:167], v[130:131], off nt
.LBB0_809:
	global_load_dwordx4 v[172:175], v[132:133], off offset:256 nt
	v_mov_b32_e32 v156, 0
	s_and_b64 vcc, exec, s[4:5]
	v_mov_b32_e32 v168, 0
	v_mov_b32_e32 v169, 0
	v_mov_b32_e32 v170, 0
	v_mov_b32_e32 v171, 0
	s_cbranch_vccnz .LBB0_811
	global_load_dwordx4 v[168:171], v[130:131], off offset:256 nt
.LBB0_811:
	v_or_b32_e32 v130, 32, v216
	v_ashrrev_i32_e32 v131, 31, v130
	v_lshlrev_b64 v[132:133], 14, v[130:131]
	v_lshl_add_u64 v[132:133], v[218:219], 0, v[132:133]
	global_load_dwordx4 v[160:163], v[132:133], off nt
	v_lshlrev_b64 v[224:225], 12, v[130:131]
	v_lshl_add_u64 v[130:131], v[220:221], 0, v[224:225]
	s_and_b64 vcc, exec, s[4:5]
	v_mov_b32_e32 v157, 0
	v_mov_b32_e32 v158, 0
	v_mov_b32_e32 v159, 0
	s_cbranch_vccnz .LBB0_813
	global_load_dwordx4 v[156:159], v[130:131], off nt
.LBB0_813:
	global_load_dwordx4 v[152:155], v[132:133], off offset:256 nt
	v_mov_b32_e32 v140, 0
	s_and_b64 vcc, exec, s[4:5]
	v_mov_b32_e32 v148, 0
	v_mov_b32_e32 v149, 0
	v_mov_b32_e32 v150, 0
	v_mov_b32_e32 v151, 0
	s_cbranch_vccnz .LBB0_815
	global_load_dwordx4 v[148:151], v[130:131], off offset:256 nt
.LBB0_815:
	v_or_b32_e32 v132, 48, v216
	v_ashrrev_i32_e32 v133, 31, v132
	v_lshlrev_b64 v[130:131], 14, v[132:133]
	v_lshl_add_u64 v[130:131], v[218:219], 0, v[130:131]
	global_load_dwordx4 v[144:147], v[130:131], off nt
	v_lshlrev_b64 v[222:223], 12, v[132:133]
	v_lshl_add_u64 v[230:231], v[220:221], 0, v[222:223]
	s_and_b64 vcc, exec, s[4:5]
	v_mov_b32_e32 v141, 0
	v_mov_b32_e32 v142, 0
	v_mov_b32_e32 v143, 0
	s_cbranch_vccnz .LBB0_817
	global_load_dwordx4 v[140:143], v[230:231], off nt
.LBB0_817:
	global_load_dwordx4 v[136:139], v[130:131], off offset:256 nt
	v_mov_b32_e32 v130, 0
	s_and_b64 vcc, exec, s[4:5]
	v_mov_b32_e32 v132, 0
	v_mov_b32_e32 v133, 0
	v_mov_b32_e32 v134, 0
	v_mov_b32_e32 v135, 0
	s_cbranch_vccnz .LBB0_819
	global_load_dwordx4 v[132:135], v[230:231], off offset:256 nt
